# phase-15 loop edge: padded waits after the wave-group test in the fast tail and the dispatch shortened (s_nop 3 to s_nop 0, byte-neutral)
# speedup vs baseline: 1.0070x; 1.0070x over previous
; __device__ __forceinline__ void phase_nsa_sw(const Params& p, u16* sm) {
;     ...
;       nsa_qk(s, cK, qf, fr, fq);
;       {
;         const bool is_sel = (v < 64);
;         const int kt = is_sel ? v : v - 64;
;         const bool lv = is_sel ? (bool)((mymask >> v) & 1ull) : true;
;         const bool masked = is_sel ? (v == (t0 >> 6)) : !((64 * kt + 63 <= t0) && (64 * kt >= t0 - 480));
;         if (masked) {
;           const int wnd = is_sel ? (1 << 30) : 512;
;           unsigned vmask = 0;
; #pragma unroll
;           for (int mt = 0; mt < 4; ++mt)
; #pragma unroll
;             for (int j = 0; j < 4; ++j) {
;               const int key = kt * 64 + 32 * (mt >> 1) + 8 * fq + 4 * (mt & 1) + j;
;               const int diff = myt - key;
;               vmask |= ((lv && diff >= 0 && diff < wnd) ? 1u : 0u) << (mt * 4 + j);
;             }
;           nsa_online_step<true>(st, s, vmask, true, cV, fr, fq);
;         } else {
;           nsa_online_step<false>(st, s, 0u, lv, cV, fr, fq);
;         }
.Lfp15_dispatch:
	s_nop 0
	s_cmp_gt_i32 s14, 63
	s_cbranch_scc1 .Lfp15_win
	s_cmp_eq_u32 s14, s45
	s_cbranch_scc0 .Lfp15_body
	s_branch .Lfp15m_body

; __device__ __forceinline__ void phase_nsa_sw(const Params& p, u16* sm) {
;     ...
;     for (int i = 0; i < ntl; ++i) {
;       __syncthreads();
;       const int v = lst[i];
;       const u16* cK = sK + (i & 1) * 2 * 64 * LDSP;
;       const u16* cV = sV + (i & 1) * 2 * 64 * LDSP;
;       if (i == nsel) {
.Lfp15_tail:
	s_add_i32 s10, s42, 1
	v_cmp_ge_i32_e64 s[8:9], s10, v231
	s_add_i32 s83, s83, 4
	s_addk_i32 s89, 0x80
	s_and_b64 vcc, exec, s[8:9]
	s_cbranch_vccnz .LBB0_1323
	s_mov_b32 s42, s10
	v_readfirstlane_b32 s11, v192
	s_nop 0
	s_cmp_lt_u32 s11, 0x100
	s_cbranch_scc1 .LBB0_1336
	v_readlane_b32 s14, v24, s42
	v_readlane_b32 s15, v25, s42
	v_cmp_ne_u32_e32 vcc, s42, v203
	s_cmp_lt_u32 s42, 64
	s_cselect_b32 s14, s14, s15
	s_cbranch_vccz .Lfp15_park
	s_branch .Lfp15_dispatch
	s_nop 0
	s_nop 0
	s_nop 0
	s_nop 0
	s_nop 0
	s_nop 0
	s_nop 0
	s_nop 0
	s_nop 0
	s_nop 0
	s_nop 0
	s_nop 0
	s_nop 0
	s_nop 0
	s_nop 0
